# latent Hyena K loop: first two B fragments of each iteration requested one iteration ahead (register moves at the loop top) on top of the transposed Hyena epilogue
# baseline (speedup 1.0000x reference)
.LBB0_1137:
	s_andn2_b64 vcc, exec, s[34:35]
	s_cbranch_vccnz .LBB0_1141
	s_ashr_i32 s34, s13, 2
	v_mov_b32_e32 v0, v218
	v_mov_b32_e32 v1, v218
	s_add_i32 s36, s34, s42
	s_lshl_b32 s13, s13, 9
	s_ashr_i32 s37, s36, 31
	s_mul_i32 s38, s36, 0x4040
	v_readlane_b32 s16, v254, 47
	v_lshlrev_b32_e32 v1, 1, v1
	s_mul_hi_i32 s35, s36, 0x4040
	v_readlane_b32 s17, v254, 48
	s_add_u32 s38, s16, s38
	v_and_b32_e32 v1, 0xffffff80, v1
	s_addc_u32 s39, s17, s35
	s_and_b32 s13, s13, 0x600
	v_add_u32_e32 v63, s13, v1
	v_and_b32_e32 v62, 15, v0
	v_bfe_u32 v64, v0, 4, 2
	v_bfe_i32 v0, v0, 0, 1
	v_lshlrev_b32_e32 v1, 3, v64
	v_and_b32_e32 v172, 0x201e, v0
	v_or_b32_e32 v0, v63, v62
	v_sub_u32_e32 v58, v1, v0
	v_lshl_add_u64 v[56:57], s[38:39], 0, v[172:173]
	v_ashrrev_i32_e32 v59, 31, v58
	v_lshl_add_u64 v[0:1], v[58:59], 1, v[56:57]
	global_load_dwordx4 v[40:43], v[0:1], off offset:4032
	global_load_dwordx4 v[44:47], v[0:1], off offset:4000
	global_load_dwordx4 v[32:35], v[0:1], off offset:3968
	global_load_dwordx4 v[36:39], v[0:1], off offset:3936
	global_load_dwordx4 v[48:51], v[0:1], off offset:3904
	global_load_dwordx4 v[52:55], v[0:1], off offset:3872
	s_lshl_b32 s35, s34, 4
	v_or_b32_e32 v59, s35, v62
	v_mad_i64_i32 v[0:1], s[38:39], v59, s9, 0
	v_readlane_b32 s16, v255, 56
	v_lshl_or_b32 v0, v64, 4, v0
	v_readlane_b32 s17, v255, 57
	v_mov_b32_e32 v28, 0
	s_mov_b64 s[46:47], s[20:21]
	s_movk_i32 s13, 0xff80
	v_lshl_add_u64 v[60:61], s[16:17], 0, v[0:1]
	v_mov_b32_e32 v29, v28
	v_mov_b32_e32 v30, v28
	v_mov_b32_e32 v31, v28
	v_mov_b32_e32 v24, v28
	v_mov_b32_e32 v25, v28
	v_mov_b32_e32 v26, v28
	v_mov_b32_e32 v27, v28
	v_mov_b32_e32 v20, v28
	v_mov_b32_e32 v21, v28
	v_mov_b32_e32 v22, v28
	v_mov_b32_e32 v23, v28
	v_mov_b32_e32 v16, v28
	v_mov_b32_e32 v17, v28
	v_mov_b32_e32 v18, v28
	v_mov_b32_e32 v19, v28
	v_mov_b32_e32 v12, v28
	v_mov_b32_e32 v13, v28
	v_mov_b32_e32 v14, v28
	v_mov_b32_e32 v15, v28
	v_mov_b32_e32 v8, v28
	v_mov_b32_e32 v9, v28
	v_mov_b32_e32 v10, v28
	v_mov_b32_e32 v11, v28
	v_mov_b32_e32 v4, v28
	v_mov_b32_e32 v5, v28
	v_mov_b32_e32 v6, v28
	v_mov_b32_e32 v7, v28
	v_mov_b32_e32 v0, v28
	v_mov_b32_e32 v1, v28
	v_mov_b32_e32 v2, v28
	v_mov_b32_e32 v3, v28
	global_load_dwordx4 v[82:85], v[60:61], off offset:-192
	global_load_dwordx4 v[86:89], v[60:61], off offset:-128
.LBB0_1139:
	s_waitcnt vmcnt(0)
	v_mov_b64_e32 v[66:67], v[82:83]
	v_mov_b64_e32 v[68:69], v[84:85]
	v_mov_b64_e32 v[70:71], v[86:87]
	v_mov_b64_e32 v[72:73], v[88:89]
	global_load_dwordx4 v[82:85], v[60:61], off offset:64
	global_load_dwordx4 v[86:89], v[60:61], off offset:128
	s_mov_b64 s[38:39], 0x100
	s_nop 1
	v_mfma_f32_16x16x32_bf16 v[4:7], v[48:51], v[66:69], v[4:7]
	v_add_u32_e32 v49, s13, v58
	v_add_u32_e32 v48, 0x880, v49
	v_add_u32_e32 v50, 0x870, v49
	v_mfma_f32_16x16x32_bf16 v[0:3], v[52:55], v[66:69], v[0:3]
	v_ashrrev_i32_e32 v49, 31, v48
	v_ashrrev_i32_e32 v51, 31, v50
	v_lshl_add_u64 v[78:79], v[48:49], 1, v[56:57]
	v_lshl_add_u64 v[80:81], v[50:51], 1, v[56:57]
	v_mfma_f32_16x16x32_bf16 v[12:15], v[32:35], v[66:69], v[12:15]
	global_load_dwordx4 v[48:51], v[78:79], off offset:64
	global_load_dwordx4 v[52:55], v[80:81], off offset:64
	s_addk_i32 s13, 0x80
	v_mfma_f32_16x16x32_bf16 v[8:11], v[36:39], v[66:69], v[8:11]
	s_cmpk_lt_u32 s13, 0x780
	global_load_dwordx4 v[74:77], v[60:61], off
	v_mfma_f32_16x16x32_bf16 v[4:7], v[32:35], v[70:73], v[4:7]
	global_load_dwordx4 v[32:35], v[78:79], off
	v_mfma_f32_16x16x32_bf16 v[0:3], v[36:39], v[70:73], v[0:3]
	global_load_dwordx4 v[36:39], v[80:81], off
	v_mfma_f32_16x16x32_bf16 v[20:23], v[40:43], v[66:69], v[20:23]
	v_mfma_f32_16x16x32_bf16 v[16:19], v[44:47], v[66:69], v[16:19]
	s_waitcnt vmcnt(1)
	v_mfma_f32_16x16x32_bf16 v[28:31], v[32:35], v[66:69], v[28:31]
	s_waitcnt vmcnt(0)
	v_mfma_f32_16x16x32_bf16 v[24:27], v[36:39], v[66:69], v[24:27]
	global_load_dwordx4 v[66:69], v[60:61], off offset:-64
	v_lshl_add_u64 v[60:61], v[60:61], 0, s[38:39]
	v_mfma_f32_16x16x32_bf16 v[12:15], v[40:43], v[70:73], v[12:15]
	v_mfma_f32_16x16x32_bf16 v[8:11], v[44:47], v[70:73], v[8:11]
	v_mfma_f32_16x16x32_bf16 v[20:23], v[32:35], v[70:73], v[20:23]
	v_mfma_f32_16x16x32_bf16 v[16:19], v[36:39], v[70:73], v[16:19]
	v_mfma_f32_16x16x32_bf16 v[28:31], v[48:51], v[70:73], v[28:31]
	v_mfma_f32_16x16x32_bf16 v[24:27], v[52:55], v[70:73], v[24:27]
	s_waitcnt vmcnt(0)
	v_mfma_f32_16x16x32_bf16 v[4:7], v[40:43], v[66:69], v[4:7]
	global_load_dwordx4 v[40:43], v[78:79], off offset:192
	v_mfma_f32_16x16x32_bf16 v[0:3], v[44:47], v[66:69], v[0:3]
	global_load_dwordx4 v[44:47], v[80:81], off offset:192
	v_mfma_f32_16x16x32_bf16 v[12:15], v[32:35], v[66:69], v[12:15]
	v_mfma_f32_16x16x32_bf16 v[8:11], v[36:39], v[66:69], v[8:11]
	v_mfma_f32_16x16x32_bf16 v[4:7], v[32:35], v[74:77], v[4:7]
	global_load_dwordx4 v[32:35], v[78:79], off offset:128
	v_mfma_f32_16x16x32_bf16 v[0:3], v[36:39], v[74:77], v[0:3]
	global_load_dwordx4 v[36:39], v[80:81], off offset:128
	v_mfma_f32_16x16x32_bf16 v[20:23], v[48:51], v[66:69], v[20:23]
	v_mfma_f32_16x16x32_bf16 v[16:19], v[52:55], v[66:69], v[16:19]
	v_mfma_f32_16x16x32_bf16 v[12:15], v[48:51], v[74:77], v[12:15]
	v_mfma_f32_16x16x32_bf16 v[8:11], v[52:55], v[74:77], v[8:11]
	s_waitcnt vmcnt(1)
	v_mfma_f32_16x16x32_bf16 v[28:31], v[32:35], v[66:69], v[28:31]
	s_waitcnt vmcnt(0)
	v_mfma_f32_16x16x32_bf16 v[24:27], v[36:39], v[66:69], v[24:27]
	v_mfma_f32_16x16x32_bf16 v[20:23], v[32:35], v[74:77], v[20:23]
	v_mfma_f32_16x16x32_bf16 v[16:19], v[36:39], v[74:77], v[16:19]
	v_mfma_f32_16x16x32_bf16 v[28:31], v[40:43], v[74:77], v[28:31]
	v_mfma_f32_16x16x32_bf16 v[24:27], v[44:47], v[74:77], v[24:27]
	s_cbranch_scc1 .LBB0_1139
	s_waitcnt vmcnt(0)
	v_mov_b64_e32 v[32:33], s[96:97]
	v_mad_i64_i32 v[32:33], s[38:39], v59, s9, v[32:33]
	s_mov_b64 s[38:39], 0x15600200
	s_ashr_i32 s35, s34, 31
	v_lshl_add_u64 v[32:33], v[32:33], 0, s[38:39]
	s_lshl_b64 s[38:39], s[34:35], 2
	s_add_u32 s38, s43, s38
	s_addc_u32 s39, s44, s39
	global_load_dword v38, v173, s[38:39]
	global_load_dword v39, v173, s[38:39] offset:1024
	global_load_dword v40, v173, s[38:39] offset:2048
	global_load_dword v41, v173, s[38:39] offset:3072
	v_mov_b32_e32 v92, 0x1000
	global_load_dword v42, v92, s[38:39]
	global_load_dword v43, v92, s[38:39] offset:1024
	global_load_dword v44, v92, s[38:39] offset:2048
	global_load_dword v45, v92, s[38:39] offset:3072
	v_mov_b32_e32 v92, 0x2000
	global_load_dword v46, v92, s[38:39]
	global_load_dword v47, v92, s[38:39] offset:1024
	global_load_dword v48, v92, s[38:39] offset:2048
	global_load_dword v49, v92, s[38:39] offset:3072
	v_mov_b32_e32 v92, 0x3000
	global_load_dword v50, v92, s[38:39]
	global_load_dword v51, v92, s[38:39] offset:1024
	global_load_dword v52, v92, s[38:39] offset:2048
	global_load_dword v53, v92, s[38:39] offset:3072
	v_mov_b32_e32 v92, 0x4000
	global_load_dword v54, v92, s[38:39]
	global_load_dword v55, v92, s[38:39] offset:1024
	global_load_dword v56, v92, s[38:39] offset:2048
	global_load_dword v57, v92, s[38:39] offset:3072
	v_mov_b32_e32 v92, 0x5000
	global_load_dword v58, v92, s[38:39]
	global_load_dword v65, v92, s[38:39] offset:1024
	global_load_dword v66, v92, s[38:39] offset:2048
	global_load_dword v67, v92, s[38:39] offset:3072
	v_mov_b32_e32 v92, 0x6000
	global_load_dword v68, v92, s[38:39]
	global_load_dword v69, v92, s[38:39] offset:1024
	global_load_dword v70, v92, s[38:39] offset:2048
	global_load_dword v71, v92, s[38:39] offset:3072
	v_mov_b32_e32 v92, 0x7000
	global_load_dword v72, v92, s[38:39]
	global_load_dword v73, v92, s[38:39] offset:1024
	global_load_dword v74, v92, s[38:39] offset:2048
	global_load_dword v75, v92, s[38:39] offset:3072
	v_readlane_b32 s16, v254, 29
	s_lshl_b64 s[36:37], s[36:37], 2
	v_readlane_b32 s18, v254, 31
	v_readlane_b32 s19, v254, 32
	s_add_u32 s36, s18, s36
	s_addc_u32 s37, s19, s37
	global_load_dword v37, v173, s[36:37]
	s_movk_i32 s13, 0x900
	v_lshl_or_b32 v34, v64, 2, v63
	v_mov_b32_e32 v35, 0x100
	v_mad_u32_u24 v172, v62, s13, v35
	v_mov_b32_e32 v35, 0
	v_lshl_add_u64 v[94:95], v[34:35], 1, v[32:33]
	global_load_dwordx2 v[76:77], v[94:95], off
	global_load_dwordx2 v[78:79], v[94:95], off offset:32
	global_load_dwordx2 v[80:81], v[94:95], off offset:64
	global_load_dwordx2 v[82:83], v[94:95], off offset:96
	global_load_dwordx2 v[84:85], v[94:95], off offset:128
	global_load_dwordx2 v[86:87], v[94:95], off offset:160
	global_load_dwordx2 v[88:89], v[94:95], off offset:192
	global_load_dwordx2 v[90:91], v[94:95], off offset:224
	v_readlane_b32 s17, v254, 30
	s_lshl_b64 s[34:35], s[34:35], 1
	v_readlane_b32 s16, v255, 42
	v_readlane_b32 s17, v255, 43
	v_readlane_b32 s20, v254, 33
	v_readlane_b32 s21, v254, 34
	v_readlane_b32 s24, v254, 37
	v_readlane_b32 s18, v254, 10
	s_mov_b64 s[20:21], s[46:47]
	s_mov_b32 s24, s64
	v_readlane_b32 s22, v254, 35
	v_readlane_b32 s23, v254, 36
	v_readlane_b32 s25, v254, 38
	v_readlane_b32 s26, v254, 39
	v_readlane_b32 s27, v254, 40
	v_readlane_b32 s28, v254, 41
	v_readlane_b32 s29, v254, 42
	v_readlane_b32 s30, v254, 43
	v_readlane_b32 s31, v254, 44
	v_readlane_b32 s19, v254, 11
	s_add_u32 s38, s16, s34
	s_addc_u32 s39, s17, s35
	s_add_u32 s36, s6, s34
	s_addc_u32 s37, s7, s35
	v_lshlrev_b32_e32 v142, 13, v62
	v_lshl_add_u32 v142, v34, 2, v142
	s_waitcnt vmcnt(0)
	v_add_f32_e32 v36, 0, v38
	v_add_f32_e32 v36, v36, v39
	v_add_f32_e32 v36, v36, v40
	v_add_f32_e32 v36, v36, v41
	v_add_f32_e32 v36, v36, v42
	v_add_f32_e32 v36, v36, v43
	v_add_f32_e32 v36, v36, v44
	v_add_f32_e32 v36, v36, v45
	v_add_f32_e32 v36, v36, v46
	v_add_f32_e32 v36, v36, v47
	v_add_f32_e32 v36, v36, v48
	v_add_f32_e32 v36, v36, v49
	v_add_f32_e32 v36, v36, v50
	v_add_f32_e32 v36, v36, v51
	v_add_f32_e32 v36, v36, v52
	v_add_f32_e32 v36, v36, v53
	v_add_f32_e32 v36, v36, v54
	v_add_f32_e32 v36, v36, v55
	v_add_f32_e32 v36, v36, v56
	v_add_f32_e32 v36, v36, v57
	v_add_f32_e32 v36, v36, v58
	v_add_f32_e32 v36, v36, v65
	v_add_f32_e32 v36, v36, v66
	v_add_f32_e32 v36, v36, v67
	v_add_f32_e32 v36, v36, v68
	v_add_f32_e32 v36, v36, v69
	v_add_f32_e32 v36, v36, v70
	v_add_f32_e32 v36, v36, v71
	v_add_f32_e32 v36, v36, v72
	v_add_f32_e32 v36, v36, v73
	v_add_f32_e32 v36, v36, v74
	v_add_f32_e32 v36, v36, v75
	s_mov_b32 s13, 0x800000
	v_add_f32_e32 v36, 0x358637bd, v36
	v_cmp_gt_f32_e32 vcc, s13, v36
	v_mul_f32_e32 v35, 0x4b800000, v36
	s_movk_i32 s13, 0x900
	s_nop 0
	v_cndmask_b32_e32 v36, v36, v35, vcc
	v_rsq_f32_e32 v36, v36
	s_nop 0
	v_mul_f32_e32 v35, 0x45800000, v36
	v_cndmask_b32_e32 v36, v36, v35, vcc
	v_lshlrev_b32_e32 v92, 16, v76
	v_mul_f32_e32 v92, v37, v92
	v_fmac_f32_e32 v92, v28, v36
	v_mov_b32_e32 v28, v92
	v_and_b32_e32 v92, 0xffff0000, v76
	v_mul_f32_e32 v92, v37, v92
	v_fmac_f32_e32 v92, v29, v36
	v_mov_b32_e32 v29, v92
	v_lshlrev_b32_e32 v92, 16, v77
	v_mul_f32_e32 v92, v37, v92
	v_fmac_f32_e32 v92, v30, v36
	v_mov_b32_e32 v30, v92
	v_and_b32_e32 v92, 0xffff0000, v77
	v_mul_f32_e32 v92, v37, v92
	v_fmac_f32_e32 v92, v31, v36
	v_mov_b32_e32 v31, v92
	v_lshlrev_b32_e32 v92, 16, v78
	v_mul_f32_e32 v92, v37, v92
	v_fmac_f32_e32 v92, v24, v36
	v_mov_b32_e32 v24, v92
	v_and_b32_e32 v92, 0xffff0000, v78
	v_mul_f32_e32 v92, v37, v92
	v_fmac_f32_e32 v92, v25, v36
	v_mov_b32_e32 v25, v92
	v_lshlrev_b32_e32 v92, 16, v79
	v_mul_f32_e32 v92, v37, v92
	v_fmac_f32_e32 v92, v26, v36
	v_mov_b32_e32 v26, v92
	v_and_b32_e32 v92, 0xffff0000, v79
	v_mul_f32_e32 v92, v37, v92
	v_fmac_f32_e32 v92, v27, v36
	v_mov_b32_e32 v27, v92
	v_lshlrev_b32_e32 v92, 16, v80
	v_mul_f32_e32 v92, v37, v92
	v_fmac_f32_e32 v92, v20, v36
	v_mov_b32_e32 v20, v92
	v_and_b32_e32 v92, 0xffff0000, v80
	v_mul_f32_e32 v92, v37, v92
	v_fmac_f32_e32 v92, v21, v36
	v_mov_b32_e32 v21, v92
	v_lshlrev_b32_e32 v92, 16, v81
	v_mul_f32_e32 v92, v37, v92
	v_fmac_f32_e32 v92, v22, v36
	v_mov_b32_e32 v22, v92
	v_and_b32_e32 v92, 0xffff0000, v81
	v_mul_f32_e32 v92, v37, v92
	v_fmac_f32_e32 v92, v23, v36
	v_mov_b32_e32 v23, v92
	v_lshlrev_b32_e32 v92, 16, v82
	v_mul_f32_e32 v92, v37, v92
	v_fmac_f32_e32 v92, v16, v36
	v_mov_b32_e32 v16, v92
	v_and_b32_e32 v92, 0xffff0000, v82
	v_mul_f32_e32 v92, v37, v92
	v_fmac_f32_e32 v92, v17, v36
	v_mov_b32_e32 v17, v92
	v_lshlrev_b32_e32 v92, 16, v83
	v_mul_f32_e32 v92, v37, v92
	v_fmac_f32_e32 v92, v18, v36
	v_mov_b32_e32 v18, v92
	v_and_b32_e32 v92, 0xffff0000, v83
	v_mul_f32_e32 v92, v37, v92
	v_fmac_f32_e32 v92, v19, v36
	v_mov_b32_e32 v19, v92
	v_lshlrev_b32_e32 v92, 16, v84
	v_mul_f32_e32 v92, v37, v92
	v_fmac_f32_e32 v92, v12, v36
	v_mov_b32_e32 v12, v92
	v_and_b32_e32 v92, 0xffff0000, v84
	v_mul_f32_e32 v92, v37, v92
	v_fmac_f32_e32 v92, v13, v36
	v_mov_b32_e32 v13, v92
	v_lshlrev_b32_e32 v92, 16, v85
	v_mul_f32_e32 v92, v37, v92
	v_fmac_f32_e32 v92, v14, v36
	v_mov_b32_e32 v14, v92
	v_and_b32_e32 v92, 0xffff0000, v85
	v_mul_f32_e32 v92, v37, v92
	v_fmac_f32_e32 v92, v15, v36
	v_mov_b32_e32 v15, v92
	v_lshlrev_b32_e32 v92, 16, v86
	v_mul_f32_e32 v92, v37, v92
	v_fmac_f32_e32 v92, v8, v36
	v_mov_b32_e32 v8, v92
	v_and_b32_e32 v92, 0xffff0000, v86
	v_mul_f32_e32 v92, v37, v92
	v_fmac_f32_e32 v92, v9, v36
	v_mov_b32_e32 v9, v92
	v_lshlrev_b32_e32 v92, 16, v87
	v_mul_f32_e32 v92, v37, v92
	v_fmac_f32_e32 v92, v10, v36
	v_mov_b32_e32 v10, v92
	v_and_b32_e32 v92, 0xffff0000, v87
	v_mul_f32_e32 v92, v37, v92
	v_fmac_f32_e32 v92, v11, v36
	v_mov_b32_e32 v11, v92
	v_lshlrev_b32_e32 v92, 16, v88
	v_mul_f32_e32 v92, v37, v92
	v_fmac_f32_e32 v92, v4, v36
	v_mov_b32_e32 v4, v92
	v_and_b32_e32 v92, 0xffff0000, v88
	v_mul_f32_e32 v92, v37, v92
	v_fmac_f32_e32 v92, v5, v36
	v_mov_b32_e32 v5, v92
	v_lshlrev_b32_e32 v92, 16, v89
	v_mul_f32_e32 v92, v37, v92
	v_fmac_f32_e32 v92, v6, v36
	v_mov_b32_e32 v6, v92
	v_and_b32_e32 v92, 0xffff0000, v89
	v_mul_f32_e32 v92, v37, v92
	v_fmac_f32_e32 v92, v7, v36
	v_mov_b32_e32 v7, v92
	v_lshlrev_b32_e32 v92, 16, v90
	v_mul_f32_e32 v92, v37, v92
	v_fmac_f32_e32 v92, v0, v36
	v_mov_b32_e32 v0, v92
	v_and_b32_e32 v92, 0xffff0000, v90
	v_mul_f32_e32 v92, v37, v92
	v_fmac_f32_e32 v92, v1, v36
	v_mov_b32_e32 v1, v92
	v_lshlrev_b32_e32 v92, 16, v91
	v_mul_f32_e32 v92, v37, v92
	v_fmac_f32_e32 v92, v2, v36
	v_mov_b32_e32 v2, v92
	v_and_b32_e32 v92, 0xffff0000, v91
	v_mul_f32_e32 v92, v37, v92
	v_fmac_f32_e32 v92, v3, v36
	v_mov_b32_e32 v3, v92
	s_lshl_b32 s38, s34, 16
	s_add_u32 s38, s96, s38
	s_addc_u32 s39, s97, 0
	global_store_dwordx4 v142, v[28:31], s[38:39]
	global_store_dwordx4 v142, v[24:27], s[38:39] offset:64
	global_store_dwordx4 v142, v[20:23], s[38:39] offset:128
	global_store_dwordx4 v142, v[16:19], s[38:39] offset:192
	global_store_dwordx4 v142, v[12:15], s[38:39] offset:256
	global_store_dwordx4 v142, v[8:11], s[38:39] offset:320
	global_store_dwordx4 v142, v[4:7], s[38:39] offset:384
	global_store_dwordx4 v142, v[0:3], s[38:39] offset:448
